# MLA attention: in all four 64-key sub-tile blocks the P.V MFMAs are interleaved into the exp block (V fragments read first into spare VGPRs, exps issued per P fragment, row sum by scalar adds); later
# speedup vs baseline: 1.0036x; 1.0036x over previous
.LBB0_367:
	s_waitcnt lgkmcnt(0)
	v_add_u32_e32 v181, 0xd000, v2
	ds_read_b64_tr_b16 v[182:183], v2 offset:61440
	ds_read_b64_tr_b16 v[184:185], v2 offset:61952
	ds_read_b64_tr_b16 v[186:187], v181 offset:12288
	ds_read_b64_tr_b16 v[188:189], v181 offset:12800
	ds_read_b64_tr_b16 v[190:191], v2 offset:62464
	ds_read_b64_tr_b16 v[192:193], v2 offset:62976
	ds_read_b64_tr_b16 v[194:195], v181 offset:13312
	ds_read_b64_tr_b16 v[196:197], v181 offset:13824
	ds_read_b64_tr_b16 v[198:199], v2 offset:63488
	ds_read_b64_tr_b16 v[200:201], v2 offset:64000
	ds_read_b64_tr_b16 v[202:203], v181 offset:14336
	ds_read_b64_tr_b16 v[204:205], v181 offset:14848
	ds_read_b64_tr_b16 v[206:207], v2 offset:64512
	ds_read_b64_tr_b16 v[208:209], v2 offset:65024
	ds_read_b64_tr_b16 v[210:211], v181 offset:15360
	ds_read_b64_tr_b16 v[212:213], v181 offset:15872
	v_exp_f32_e32 v218, v80
	v_exp_f32_e32 v219, v81
	v_exp_f32_e32 v220, v82
	v_exp_f32_e32 v221, v83
	v_exp_f32_e32 v222, v84
	v_exp_f32_e32 v223, v85
	v_exp_f32_e32 v224, v86
	v_exp_f32_e32 v225, v87
	v_cvt_pk_bf16_f32 v226, v218, v219
	v_cvt_pk_bf16_f32 v227, v220, v221
	v_cvt_pk_bf16_f32 v228, v222, v223
	v_cvt_pk_bf16_f32 v229, v224, v225
	v_mov_b32_e32 v242, v218
	v_mov_b32_e32 v246, v219
	v_add_f32_e32 v242, v242, v220
	v_add_f32_e32 v246, v246, v221
	v_add_f32_e32 v242, v242, v222
	v_add_f32_e32 v246, v246, v223
	v_add_f32_e32 v242, v242, v224
	v_add_f32_e32 v246, v246, v225
	s_waitcnt lgkmcnt(12)
	v_mfma_f32_32x32x16_bf16 v[48:63], v[182:185], v[226:229], v[48:63]
	v_mfma_f32_32x32x16_bf16 v[32:47], v[186:189], v[226:229], v[32:47]
	v_exp_f32_e32 v218, v88
	v_exp_f32_e32 v219, v89
	v_exp_f32_e32 v220, v90
	v_exp_f32_e32 v221, v91
	v_exp_f32_e32 v222, v92
	v_exp_f32_e32 v223, v93
	v_exp_f32_e32 v224, v94
	v_exp_f32_e32 v225, v95
	v_cvt_pk_bf16_f32 v230, v218, v219
	v_cvt_pk_bf16_f32 v231, v220, v221
	v_cvt_pk_bf16_f32 v232, v222, v223
	v_cvt_pk_bf16_f32 v233, v224, v225
	v_add_f32_e32 v242, v242, v218
	v_add_f32_e32 v246, v246, v219
	v_add_f32_e32 v242, v242, v220
	v_add_f32_e32 v246, v246, v221
	v_add_f32_e32 v242, v242, v222
	v_add_f32_e32 v246, v246, v223
	v_add_f32_e32 v242, v242, v224
	v_add_f32_e32 v246, v246, v225
	s_waitcnt lgkmcnt(8)
	v_mfma_f32_32x32x16_bf16 v[48:63], v[190:193], v[230:233], v[48:63]
	v_mfma_f32_32x32x16_bf16 v[32:47], v[194:197], v[230:233], v[32:47]
	v_exp_f32_e32 v218, v96
	v_exp_f32_e32 v219, v97
	v_exp_f32_e32 v220, v98
	v_exp_f32_e32 v221, v99
	v_exp_f32_e32 v222, v100
	v_exp_f32_e32 v223, v101
	v_exp_f32_e32 v224, v102
	v_exp_f32_e32 v225, v103
	v_cvt_pk_bf16_f32 v234, v218, v219
	v_cvt_pk_bf16_f32 v235, v220, v221
	v_cvt_pk_bf16_f32 v236, v222, v223
	v_cvt_pk_bf16_f32 v237, v224, v225
	v_add_f32_e32 v242, v242, v218
	v_add_f32_e32 v246, v246, v219
	v_add_f32_e32 v242, v242, v220
	v_add_f32_e32 v246, v246, v221
	v_add_f32_e32 v242, v242, v222
	v_add_f32_e32 v246, v246, v223
	v_add_f32_e32 v242, v242, v224
	v_add_f32_e32 v246, v246, v225
	s_waitcnt lgkmcnt(4)
	v_mfma_f32_32x32x16_bf16 v[48:63], v[198:201], v[234:237], v[48:63]
	v_mfma_f32_32x32x16_bf16 v[32:47], v[202:205], v[234:237], v[32:47]
	v_exp_f32_e32 v218, v104
	v_exp_f32_e32 v219, v105
	v_exp_f32_e32 v220, v106
	v_exp_f32_e32 v221, v107
	v_exp_f32_e32 v222, v108
	v_exp_f32_e32 v223, v109
	v_exp_f32_e32 v224, v110
	v_exp_f32_e32 v225, v111
	v_cvt_pk_bf16_f32 v238, v218, v219
	v_cvt_pk_bf16_f32 v239, v220, v221
	v_cvt_pk_bf16_f32 v240, v222, v223
	v_cvt_pk_bf16_f32 v241, v224, v225
	v_add_f32_e32 v242, v242, v218
	v_add_f32_e32 v246, v246, v219
	v_add_f32_e32 v242, v242, v220
	v_add_f32_e32 v246, v246, v221
	v_add_f32_e32 v242, v242, v222
	v_add_f32_e32 v246, v246, v223
	v_add_f32_e32 v242, v242, v224
	v_add_f32_e32 v246, v246, v225
	s_waitcnt lgkmcnt(0)
	v_mfma_f32_32x32x16_bf16 v[48:63], v[206:209], v[238:241], v[48:63]
	v_mfma_f32_32x32x16_bf16 v[32:47], v[210:213], v[238:241], v[32:47]
	v_add_f32_e32 v242, v242, v246
	v_add_f32_e32 v6, v6, v242
	s_andn2_b64 vcc, exec, s[4:5]
	s_cbranch_vccnz .LBB0_350
	s_branch .LBB0_374
	s_nop 0
	s_nop 0
	s_nop 0
	s_nop 0
	s_nop 0
	s_nop 0
	s_nop 0
	s_nop 0
	s_nop 0
	s_nop 0

.LBB0_372:
	s_waitcnt lgkmcnt(0)
	ds_read_b64_tr_b16 v[182:183], v2 offset:53248
	ds_read_b64_tr_b16 v[184:185], v2 offset:53760
	ds_read_b64_tr_b16 v[186:187], v2 offset:57344
	ds_read_b64_tr_b16 v[188:189], v2 offset:57856
	ds_read_b64_tr_b16 v[190:191], v2 offset:54272
	ds_read_b64_tr_b16 v[192:193], v2 offset:54784
	ds_read_b64_tr_b16 v[194:195], v2 offset:58368
	ds_read_b64_tr_b16 v[196:197], v2 offset:58880
	ds_read_b64_tr_b16 v[198:199], v2 offset:55296
	ds_read_b64_tr_b16 v[200:201], v2 offset:55808
	ds_read_b64_tr_b16 v[202:203], v2 offset:59392
	ds_read_b64_tr_b16 v[204:205], v2 offset:59904
	ds_read_b64_tr_b16 v[206:207], v2 offset:56320
	ds_read_b64_tr_b16 v[208:209], v2 offset:56832
	ds_read_b64_tr_b16 v[210:211], v2 offset:60416
	ds_read_b64_tr_b16 v[212:213], v2 offset:60928
	v_exp_f32_e32 v218, v80
	v_exp_f32_e32 v219, v81
	v_exp_f32_e32 v220, v82
	v_exp_f32_e32 v221, v83
	v_exp_f32_e32 v222, v84
	v_exp_f32_e32 v223, v85
	v_exp_f32_e32 v224, v86
	v_exp_f32_e32 v225, v87
	v_cvt_pk_bf16_f32 v226, v218, v219
	v_cvt_pk_bf16_f32 v227, v220, v221
	v_cvt_pk_bf16_f32 v228, v222, v223
	v_cvt_pk_bf16_f32 v229, v224, v225
	v_mov_b32_e32 v242, v218
	v_mov_b32_e32 v246, v219
	v_add_f32_e32 v242, v242, v220
	v_add_f32_e32 v246, v246, v221
	v_add_f32_e32 v242, v242, v222
	v_add_f32_e32 v246, v246, v223
	v_add_f32_e32 v242, v242, v224
	v_add_f32_e32 v246, v246, v225
	s_waitcnt lgkmcnt(12)
	v_mfma_f32_32x32x16_bf16 v[48:63], v[182:185], v[226:229], v[48:63]
	v_mfma_f32_32x32x16_bf16 v[32:47], v[186:189], v[226:229], v[32:47]
	v_exp_f32_e32 v218, v88
	v_exp_f32_e32 v219, v89
	v_exp_f32_e32 v220, v90
	v_exp_f32_e32 v221, v91
	v_exp_f32_e32 v222, v92
	v_exp_f32_e32 v223, v93
	v_exp_f32_e32 v224, v94
	v_exp_f32_e32 v225, v95
	v_cvt_pk_bf16_f32 v230, v218, v219
	v_cvt_pk_bf16_f32 v231, v220, v221
	v_cvt_pk_bf16_f32 v232, v222, v223
	v_cvt_pk_bf16_f32 v233, v224, v225
	v_add_f32_e32 v242, v242, v218
	v_add_f32_e32 v246, v246, v219
	v_add_f32_e32 v242, v242, v220
	v_add_f32_e32 v246, v246, v221
	v_add_f32_e32 v242, v242, v222
	v_add_f32_e32 v246, v246, v223
	v_add_f32_e32 v242, v242, v224
	v_add_f32_e32 v246, v246, v225
	s_waitcnt lgkmcnt(8)
	v_mfma_f32_32x32x16_bf16 v[48:63], v[190:193], v[230:233], v[48:63]
	v_mfma_f32_32x32x16_bf16 v[32:47], v[194:197], v[230:233], v[32:47]
	v_exp_f32_e32 v218, v96
	v_exp_f32_e32 v219, v97
	v_exp_f32_e32 v220, v98
	v_exp_f32_e32 v221, v99
	v_exp_f32_e32 v222, v100
	v_exp_f32_e32 v223, v101
	v_exp_f32_e32 v224, v102
	v_exp_f32_e32 v225, v103
	v_cvt_pk_bf16_f32 v234, v218, v219
	v_cvt_pk_bf16_f32 v235, v220, v221
	v_cvt_pk_bf16_f32 v236, v222, v223
	v_cvt_pk_bf16_f32 v237, v224, v225
	v_add_f32_e32 v242, v242, v218
	v_add_f32_e32 v246, v246, v219
	v_add_f32_e32 v242, v242, v220
	v_add_f32_e32 v246, v246, v221
	v_add_f32_e32 v242, v242, v222
	v_add_f32_e32 v246, v246, v223
	v_add_f32_e32 v242, v242, v224
	v_add_f32_e32 v246, v246, v225
	s_waitcnt lgkmcnt(4)
	v_mfma_f32_32x32x16_bf16 v[48:63], v[198:201], v[234:237], v[48:63]
	v_mfma_f32_32x32x16_bf16 v[32:47], v[202:205], v[234:237], v[32:47]
	v_exp_f32_e32 v218, v104
	v_exp_f32_e32 v219, v105
	v_exp_f32_e32 v220, v106
	v_exp_f32_e32 v221, v107
	v_exp_f32_e32 v222, v108
	v_exp_f32_e32 v223, v109
	v_exp_f32_e32 v224, v110
	v_exp_f32_e32 v225, v111
	v_cvt_pk_bf16_f32 v238, v218, v219
	v_cvt_pk_bf16_f32 v239, v220, v221
	v_cvt_pk_bf16_f32 v240, v222, v223
	v_cvt_pk_bf16_f32 v241, v224, v225
	v_add_f32_e32 v242, v242, v218
	v_add_f32_e32 v246, v246, v219
	v_add_f32_e32 v242, v242, v220
	v_add_f32_e32 v246, v246, v221
	v_add_f32_e32 v242, v242, v222
	v_add_f32_e32 v246, v246, v223
	v_add_f32_e32 v242, v242, v224
	v_add_f32_e32 v246, v246, v225
	s_waitcnt lgkmcnt(0)
	v_mfma_f32_32x32x16_bf16 v[48:63], v[206:209], v[238:241], v[48:63]
	v_mfma_f32_32x32x16_bf16 v[32:47], v[210:213], v[238:241], v[32:47]
	v_add_f32_e32 v242, v242, v246
	v_add_f32_e32 v6, v6, v242
	s_add_i32 s2, s57, 64
	s_cmp_gt_i32 s2, s54
	s_cbranch_scc0 .LBB0_363

.LBB0_376:
	s_andn2_saveexec_b64 s[4:5], s[4:5]
	s_cbranch_execz .LBB0_349
	v_add3_u32 v2, s2, v174, v176
	s_add_i32 s2, s2, s3
	ds_write_b128 v2, v[144:147] offset:128
	s_waitcnt vmcnt(1)
	ds_write_b128 v0, v[152:155] offset:13312
	v_add_u32_e32 v0, s2, v170
	v_add3_u32 v0, v0, v171, v172
	s_waitcnt vmcnt(0)
	ds_write_b128 v0, v[156:159] offset:61440
	ds_write_b128 v2, v[148:151] offset:13440
	s_branch .LBB0_349
	s_nop 0
	s_nop 0
	s_nop 0
	s_nop 0
	s_nop 0
	s_nop 0
	s_nop 0
	s_nop 0
	s_nop 0

.LBB0_410:
	s_waitcnt lgkmcnt(0)
	ds_read_b64_tr_b16 v[182:183], v2 offset:53248
	ds_read_b64_tr_b16 v[184:185], v2 offset:53760
	ds_read_b64_tr_b16 v[186:187], v2 offset:57344
	ds_read_b64_tr_b16 v[188:189], v2 offset:57856
	ds_read_b64_tr_b16 v[190:191], v2 offset:54272
	ds_read_b64_tr_b16 v[192:193], v2 offset:54784
	ds_read_b64_tr_b16 v[194:195], v2 offset:58368
	ds_read_b64_tr_b16 v[196:197], v2 offset:58880
	ds_read_b64_tr_b16 v[198:199], v2 offset:55296
	ds_read_b64_tr_b16 v[200:201], v2 offset:55808
	ds_read_b64_tr_b16 v[202:203], v2 offset:59392
	ds_read_b64_tr_b16 v[204:205], v2 offset:59904
	ds_read_b64_tr_b16 v[206:207], v2 offset:56320
	ds_read_b64_tr_b16 v[208:209], v2 offset:56832
	ds_read_b64_tr_b16 v[210:211], v2 offset:60416
	ds_read_b64_tr_b16 v[212:213], v2 offset:60928
	v_exp_f32_e32 v218, v80
	v_exp_f32_e32 v219, v81
	v_exp_f32_e32 v220, v82
	v_exp_f32_e32 v221, v83
	v_exp_f32_e32 v222, v84
	v_exp_f32_e32 v223, v85
	v_exp_f32_e32 v224, v86
	v_exp_f32_e32 v225, v87
	v_cvt_pk_bf16_f32 v226, v218, v219
	v_cvt_pk_bf16_f32 v227, v220, v221
	v_cvt_pk_bf16_f32 v228, v222, v223
	v_cvt_pk_bf16_f32 v229, v224, v225
	v_mov_b32_e32 v242, v218
	v_mov_b32_e32 v246, v219
	v_add_f32_e32 v242, v242, v220
	v_add_f32_e32 v246, v246, v221
	v_add_f32_e32 v242, v242, v222
	v_add_f32_e32 v246, v246, v223
	v_add_f32_e32 v242, v242, v224
	v_add_f32_e32 v246, v246, v225
	s_waitcnt lgkmcnt(12)
	v_mfma_f32_32x32x16_bf16 v[48:63], v[182:185], v[226:229], v[48:63]
	v_mfma_f32_32x32x16_bf16 v[32:47], v[186:189], v[226:229], v[32:47]
	v_exp_f32_e32 v218, v88
	v_exp_f32_e32 v219, v89
	v_exp_f32_e32 v220, v90
	v_exp_f32_e32 v221, v91
	v_exp_f32_e32 v222, v92
	v_exp_f32_e32 v223, v93
	v_exp_f32_e32 v224, v94
	v_exp_f32_e32 v225, v95
	v_cvt_pk_bf16_f32 v230, v218, v219
	v_cvt_pk_bf16_f32 v231, v220, v221
	v_cvt_pk_bf16_f32 v232, v222, v223
	v_cvt_pk_bf16_f32 v233, v224, v225
	v_add_f32_e32 v242, v242, v218
	v_add_f32_e32 v246, v246, v219
	v_add_f32_e32 v242, v242, v220
	v_add_f32_e32 v246, v246, v221
	v_add_f32_e32 v242, v242, v222
	v_add_f32_e32 v246, v246, v223
	v_add_f32_e32 v242, v242, v224
	v_add_f32_e32 v246, v246, v225
	s_waitcnt lgkmcnt(8)
	v_mfma_f32_32x32x16_bf16 v[48:63], v[190:193], v[230:233], v[48:63]
	v_mfma_f32_32x32x16_bf16 v[32:47], v[194:197], v[230:233], v[32:47]
	v_exp_f32_e32 v218, v96
	v_exp_f32_e32 v219, v97
	v_exp_f32_e32 v220, v98
	v_exp_f32_e32 v221, v99
	v_exp_f32_e32 v222, v100
	v_exp_f32_e32 v223, v101
	v_exp_f32_e32 v224, v102
	v_exp_f32_e32 v225, v103
	v_cvt_pk_bf16_f32 v234, v218, v219
	v_cvt_pk_bf16_f32 v235, v220, v221
	v_cvt_pk_bf16_f32 v236, v222, v223
	v_cvt_pk_bf16_f32 v237, v224, v225
	v_add_f32_e32 v242, v242, v218
	v_add_f32_e32 v246, v246, v219
	v_add_f32_e32 v242, v242, v220
	v_add_f32_e32 v246, v246, v221
	v_add_f32_e32 v242, v242, v222
	v_add_f32_e32 v246, v246, v223
	v_add_f32_e32 v242, v242, v224
	v_add_f32_e32 v246, v246, v225
	s_waitcnt lgkmcnt(4)
	v_mfma_f32_32x32x16_bf16 v[48:63], v[198:201], v[234:237], v[48:63]
	v_mfma_f32_32x32x16_bf16 v[32:47], v[202:205], v[234:237], v[32:47]
	v_exp_f32_e32 v218, v104
	v_exp_f32_e32 v219, v105
	v_exp_f32_e32 v220, v106
	v_exp_f32_e32 v221, v107
	v_exp_f32_e32 v222, v108
	v_exp_f32_e32 v223, v109
	v_exp_f32_e32 v224, v110
	v_exp_f32_e32 v225, v111
	v_cvt_pk_bf16_f32 v238, v218, v219
	v_cvt_pk_bf16_f32 v239, v220, v221
	v_cvt_pk_bf16_f32 v240, v222, v223
	v_cvt_pk_bf16_f32 v241, v224, v225
	v_add_f32_e32 v242, v242, v218
	v_add_f32_e32 v246, v246, v219
	v_add_f32_e32 v242, v242, v220
	v_add_f32_e32 v246, v246, v221
	v_add_f32_e32 v242, v242, v222
	v_add_f32_e32 v246, v246, v223
	v_add_f32_e32 v242, v242, v224
	v_add_f32_e32 v246, v246, v225
	s_waitcnt lgkmcnt(0)
	v_mfma_f32_32x32x16_bf16 v[48:63], v[206:209], v[238:241], v[48:63]
	v_mfma_f32_32x32x16_bf16 v[32:47], v[210:213], v[238:241], v[32:47]
	v_add_f32_e32 v242, v242, v246
	v_add_f32_e32 v6, v6, v242
	s_add_i32 s2, s37, 64
	s_cmp_gt_i32 s2, s28
	s_cbranch_scc0 .LBB0_401
